# attention unit prologue: third K/V tile's loads issued right after the Q-stash writes instead of after the first barrier
# speedup vs baseline: 1.0098x; 1.0018x over previous
; #define LAS __attribute__((address_space(3)))
; #define ATT_BAR() asm volatile("s_waitcnt lgkmcnt(0)\n\ts_barrier" ::: "memory")
; __device__ __forceinline__ void attn_unit(LAS unsigned char* lds, const bf16* Qh, const bf16* Kh, const bf16* VTh, const float* nrm, bf16* Y, const float* subln, float lam, int b, int h, int qb) {
;     ...
;     const int tid = tid_, lane = tid & 63, r32 = lane & 31, hi = lane >> 5, wid = __builtin_amdgcn_readfirstlane(tid >> 6);
;     const int wq = wid & 3, comp = wid >> 2;
;     const size_t tokb = (size_t)b * SEQ; const int q0 = qb * 128, qw0 = q0 + wq * 32;
;     const int bh = b * 16 + h;
;     const int qso = OFF_Q + wid * 4096 + lane * 16;
;     { const bf16* qp = Qh + ((size_t)bh * 4096 + qw0 + r32) * 128 + comp * 64 + hi * 8;
; #pragma unroll
;       for (int d0 = 0; d0 < 4; ++d0) *(LAS bf16x8*)(lds + qso + d0 * 1024) = *(const bf16x8*)(qp + d0 * 16); }
;     const char* kgb = (const char*)(Kh + (size_t)bh * 4096 * 128);
;     const char* vgb = (const char*)(VTh + (size_t)bh * 4096 * 128);
;     const unsigned goff = (unsigned)tid * 16u;
;     const int kl0 = OFF_K + (tid >> 4) * KROW + (tid & 15) * 16, vl0 = OFF_V + (tid >> 3) * VROW + (tid & 7) * 16;
;     const int sig = (r32 & ~12) | ((r32 & 4) << 1) | ((r32 & 8) >> 1);
;     const int kfo = OFF_K + sig * KROW + comp * 128 + hi * 16;
;     const int vfo = OFF_V + r32 * VROW + hi * 16;
;     LAS float* wsf = (LAS float*)(lds + OFF_WS) + wid * 64;
;     LAS float* tminb = (LAS float*)(lds + OFF_TMIN);
;     const float slope2 = exp2f(-0.5f * (float)(h + 1)) * LOG2E;
;     const int qpos = qw0 + r32;
;     const int u0 = 2 * qb, u1 = 2 * qb + 1, u2 = (qb == 0) ? 2 : (qb == 31 ? 61 : 2 * qb - 1), u3 = (qb == 0) ? 3 : (qb == 31 ? 60 : 2 * qb + 2);
;     int ktv = (lane == 0) ? u0 : (lane == 1) ? u1 : (lane == 2) ? u2 : u3;
;     const float* nb = nrm + (size_t)b * 64 * 64;
;     const float k2a = nb[lane * 64 + 32 + 2 * h], k2b = nb[lane * 64 + 32 + 2 * h + 1];
;     const float q2a = fmaxf(nb[u0 * 64 + 2 * h], nb[u1 * 64 + 2 * h]), q2b = fmaxf(nb[u0 * 64 + 2 * h + 1], nb[u1 * 64 + 2 * h + 1]);
;     f32x16 o[4];
; #pragma unroll
;     for (int i = 0; i < 4; ++i) o[i] = f32x16{};
;     float mhat = 0.f, lsum = 0.f, tmax = -INFINITY; bool resc = false;
;     v4u pw[4] = {};
;     v4u kreg[2], vreg[2];
;     ...
;     ATT_LOAD(u0); ATT_STORE(0); ATT_LOAD(u1);
;     ATT_BAR();
.LBB0_911:
	s_or_b64 exec, exec, s[10:11]
	v_mov_b32_e32 v0, s94
	s_waitcnt lgkmcnt(0)
	s_barrier
	ds_read_b32 v0, v0
	s_waitcnt lgkmcnt(0)
	v_cmp_gt_i32_e32 vcc, 0, v0
	v_readfirstlane_b32 s0, v0
	s_cbranch_vccnz .LBB0_921
	s_lshr_b32 s1, s0, 8
	s_and_b32 s3, s0, 0x80
	s_sub_i32 s5, 15, s1
	v_mov_b32_e32 v6, v248
	s_cmp_eq_u32 s3, 0
	s_cselect_b32 s5, s5, s1
	v_readfirstlane_b32 s81, v6
	s_ashr_i32 s1, s81, 6
	s_and_b32 s3, s0, 31
	s_and_b32 s14, s1, 3
	s_bfe_u32 s80, s0, 0x20005
	s_lshl_b32 s0, s3, 7
	s_lshl_b32 s6, s14, 5
	s_or_b32 s18, s6, s0
	s_lshl_b32 s6, s80, 4
	s_add_i32 s6, s6, s5
	s_ashr_i32 s7, s6, 31
	s_lshl_b64 s[10:11], s[6:7], 12
	v_and_b32_e32 v202, 31, v6
	s_or_b32 s10, s10, s18
	s_ashr_i32 s15, s81, 8
	v_or_b32_e32 v0, s10, v202
	v_mov_b32_e32 v1, s11
	v_lshlrev_b64 v[0:1], 8, v[0:1]
	s_lshl_b32 s10, s15, 6
	v_bfe_u32 v201, v6, 5, 1
	v_lshl_add_u64 v[0:1], s[26:27], 0, v[0:1]
	s_ashr_i32 s11, s10, 31
	v_and_b32_e32 v203, 63, v6
	v_lshl_add_u64 v[0:1], s[10:11], 1, v[0:1]
	v_lshlrev_b32_e32 v180, 4, v201
	v_mov_b32_e32 v181, v177
	v_lshl_add_u64 v[4:5], v[0:1], 0, v[180:181]
	v_lshl_add_u32 v0, v203, 4, 0
	s_lshl_b32 s12, s1, 12
	v_add_u32_e32 v0, 0x1ac80, v0
	v_add_u32_e32 v210, s12, v0
	global_load_dwordx4 v[128:131], v[4:5], off
	global_load_dwordx4 v[132:135], v[4:5], off offset:32
	global_load_dwordx4 v[136:139], v[4:5], off offset:64
	global_load_dwordx4 v[140:143], v[4:5], off offset:96
	s_lshl_b64 s[12:13], s[6:7], 20
	s_movk_i32 s6, 0x110
	s_add_u32 s68, s38, s12
	s_addc_u32 s69, s39, s13
	s_lshl_b32 s64, s15, 7
	v_lshlrev_b32_e32 v176, 6, v203
	v_lshlrev_b32_e32 v216, 4, v6
	v_lshl_add_u32 v8, s3, 15, v216
	v_add_u32_e32 v12, 0x2000, v8
	v_and_b32_e32 v32, 0xf0, v216
	v_and_b32_e32 v34, 0x70, v216
	v_lshlrev_b32_e32 v209, 3, v201
	v_or_b32_e32 v212, s18, v202
	v_lshrrev_b32_e32 v0, 4, v6
	v_mul_lo_u32 v30, v0, s6
	v_lshrrev_b32_e32 v0, 3, v6
	v_lshlrev_b32_e32 v1, 1, v6
	v_lshrrev_b32_e32 v2, 1, v6
	v_mul_lo_u32 v31, v0, s83
	v_and_b32_e32 v0, 19, v6
	v_and_b32_e32 v1, 8, v1
	v_and_b32_e32 v2, 4, v2
	s_add_i32 s6, s5, 1
	v_or3_b32 v2, v0, v1, v2
	v_cvt_f32_i32_e32 v0, s6
	s_mov_b32 s6, 0xc2fc0000
	v_mul_u32_u24_e32 v33, 0x110, v2
	v_add3_u32 v16, 0, v30, v32
	v_mul_f32_e32 v1, -0.5, v0
	v_cmp_gt_f32_e32 vcc, s6, v1
	s_and_b64 s[6:7], vcc, exec
	s_cselect_b32 s6, 0xffffffc0, 0
	v_cndmask_b32_e32 v1, 0, v249, vcc
	v_fmac_f32_e32 v1, -0.5, v0
	v_exp_f32_e32 v0, v1
	v_cmp_eq_u32_e32 vcc, 1, v203
	v_ldexp_f32 v0, v0, s6
	s_lshl_b32 s6, s3, 1
	s_or_b32 s24, s6, 1
	s_add_i32 s7, s6, -1
	s_add_i32 s10, s6, 2
	s_cmp_lg_u32 s3, 31
	s_cselect_b32 s10, s10, 60
	s_cmp_eq_u32 s3, 0
	s_cselect_b32 s33, 2, s7
	s_cselect_b32 s25, 3, s10
	v_mul_f32_e32 v208, 0x3fb8aa3b, v0
	v_cmp_eq_u32_e64 s[10:11], 2, v203
	v_mov_b32_e32 v0, s25
	v_mov_b32_e32 v1, s33
	s_lshl_b32 s7, s80, 14
	v_cndmask_b32_e64 v0, v0, v1, s[10:11]
	s_add_u32 s10, s35, s7
	s_addc_u32 s11, s92, 0
	s_lshl_b32 s16, s5, 1
	s_add_i32 s66, s16, s0
	s_ashr_i32 s67, s66, 31
	s_ashr_i32 s17, s16, 31
	s_lshl_b64 s[66:67], s[66:67], 2
	s_add_u32 s66, s10, s66
	v_mov_b32_e32 v1, s24
	s_addc_u32 s67, s11, s67
	s_lshl_b32 s7, s24, 6
	v_cndmask_b32_e32 v3, v0, v1, vcc
	v_lshl_add_u64 v[0:1], s[16:17], 0, v[176:177]
	s_add_i32 s16, s7, s16
	s_ashr_i32 s17, s16, 31
	s_lshl_b64 s[16:17], s[16:17], 2
	v_lshl_add_u64 v[0:1], v[0:1], 2, s[10:11]
	s_add_u32 s10, s10, s16
	s_addc_u32 s11, s11, s17
	s_add_u32 s70, s42, s12
	global_load_dwordx2 v[24:25], v[0:1], off offset:128
	global_load_dwordx2 v[26:27], v177, s[66:67]
	s_addc_u32 s71, s43, s13
	v_cmp_eq_u32_e64 s[12:13], 0, v203
	v_mov_b32_e32 v0, s6
	global_load_dwordx2 v[28:29], v177, s[10:11]
	v_cndmask_b32_e64 v213, v3, v0, s[12:13]
	global_load_dwordx4 v[0:3], v8, s[70:71]
	global_load_dwordx4 v[4:7], v12, s[70:71]
	s_nop 0
	global_load_dwordx4 v[8:11], v8, s[68:69]
	s_nop 0
	global_load_dwordx4 v[12:15], v12, s[68:69]
	v_lshl_add_u32 v160, s24, 14, v216
	v_add_u32_e32 v161, 0x2000, v160
	global_load_dwordx4 v[144:147], v160, s[70:71]
	global_load_dwordx4 v[148:151], v161, s[70:71]
	global_load_dwordx4 v[152:155], v160, s[68:69]
	global_load_dwordx4 v[156:159], v161, s[68:69]
	v_readlane_b32 s3, v213, 2
	s_add_i32 s7, s64, 0
	v_add3_u32 v217, s7, v33, v180
	s_waitcnt vmcnt(11)
	ds_write_b128 v210, v[128:131]
	ds_write_b128 v210, v[132:135] offset:1024
	ds_write_b128 v210, v[136:139] offset:2048
	ds_write_b128 v210, v[140:143] offset:3072
	v_lshl_add_u32 v162, s3, 14, v216
	v_add_u32_e32 v163, 0x2000, v162
	global_load_dwordx4 v[128:131], v162, s[70:71]
	global_load_dwordx4 v[132:135], v163, s[70:71]
	global_load_dwordx4 v[136:139], v162, s[68:69]
	global_load_dwordx4 v[140:143], v163, s[68:69]
	s_waitcnt vmcnt(11)
	ds_write_b128 v16, v[0:3]
	s_waitcnt vmcnt(10)
	ds_write_b128 v16, v[4:7] offset:8704
	v_add3_u32 v0, 0, v31, v34
	s_waitcnt vmcnt(9)
	ds_write_b128 v0, v[8:11] offset:52224
	s_waitcnt vmcnt(8)
	ds_write_b128 v0, v[12:15] offset:61440
	v_add_u32_e32 v17, 0xcc00, v0
	s_waitcnt lgkmcnt(0)
	s_barrier
	s_waitcnt vmcnt(7)
	ds_write_b128 v16, v[144:147] offset:17408
	s_waitcnt vmcnt(6)
	ds_write_b128 v16, v[148:151] offset:26112
	s_waitcnt vmcnt(5)
	ds_write_b128 v17, v[152:155] offset:18432
	s_waitcnt vmcnt(4)
	ds_write_b128 v17, v[156:159] offset:27648
	v_readlane_b32 s3, v213, 0
	s_lshl_b32 s3, s3, 6
	s_or_b32 s7, s3, 63
	v_or_b32_e32 v0, s3, v209
	v_sub_u32_e32 v16, v212, v0
	ds_read_b128 v[12:15], v210
	ds_read_b128 v[8:11], v210 offset:1024
	ds_read_b128 v[4:7], v210 offset:2048
	ds_read_b128 v[0:3], v210 offset:3072
	s_cmp_lt_i32 s7, s18
	v_cvt_f32_i32_e32 v35, v16
	ds_read_b128 v[20:23], v217
	ds_read_b128 v[16:19], v217 offset:8704
	s_cselect_b64 s[10:11], -1, 0
	s_or_b32 s7, s18, 31
	s_cmp_gt_i32 s3, s7
	s_cselect_b64 s[16:17], -1, 0
	s_or_b64 s[66:67], s[10:11], s[16:17]
	s_mov_b64 s[16:17], -1
	s_andn2_b64 vcc, exec, s[66:67]
	s_cbranch_vccz .LBB0_914
	v_add_f32_e32 v36, v35, v179
	v_xor_b32_e32 v39, 0x80000000, v208
	v_add_f32_e32 v37, v36, v179
	v_fma_f32 v72, |v36|, v39, v184
	v_add_f32_e32 v40, v35, v185
	v_add_f32_e32 v36, v36, v185
	v_fma_f32 v64, |v35|, v39, v184
	s_mov_b64 s[16:17], 0
	v_add_f32_e32 v38, v37, v179
	v_fma_f32 v80, |v37|, v39, v184
	v_add_f32_e32 v37, v37, v185
	v_fma_f32 v65, |v40|, v39, v184
	v_fma_f32 v73, |v36|, v39, v184
	v_add_f32_e32 v40, v40, v185
	v_fma_f32 v88, |v38|, v39, v184
	v_add_f32_e32 v38, v38, v185
	v_fma_f32 v81, |v37|, v39, v184
	v_add_f32_e32 v36, v36, v185
	v_add_f32_e32 v37, v37, v185
	v_fma_f32 v66, |v40|, v39, v184
	v_add_f32_e32 v40, v40, v185
	v_fma_f32 v89, |v38|, v39, v184
	v_add_f32_e32 v38, v38, v185
	v_fma_f32 v74, |v36|, v39, v184
	v_fma_f32 v82, |v37|, v39, v184
	v_add_f32_e32 v36, v36, v185
	v_add_f32_e32 v37, v37, v185
	v_fma_f32 v67, |v40|, v39, v184
	v_fma_f32 v90, |v38|, v39, v184
	v_add_f32_e32 v38, v38, v185
	v_add_f32_e32 v40, v40, v185
	v_fma_f32 v75, |v36|, v39, v184
	v_fma_f32 v83, |v37|, v39, v184
	v_add_f32_e32 v36, v36, v185
	v_add_f32_e32 v37, v37, v185
	v_fma_f32 v91, |v38|, v39, v184
	v_add_f32_e32 v38, v38, v185
	v_fma_f32 v68, |v40|, v39, v184
	v_add_f32_e32 v40, v40, v185
	v_fma_f32 v76, |v36|, v39, v184
	v_fma_f32 v84, |v37|, v39, v184
	v_add_f32_e32 v36, v36, v185
	v_fma_f32 v92, |v38|, v39, v184
	v_add_f32_e32 v37, v37, v185
	v_add_f32_e32 v38, v38, v185
	v_fma_f32 v69, |v40|, v39, v184
	v_add_f32_e32 v40, v40, v185
	v_fma_f32 v77, |v36|, v39, v184
	v_add_f32_e32 v36, v36, v185
	v_fma_f32 v85, |v37|, v39, v184
	v_fma_f32 v93, |v38|, v39, v184
	v_add_f32_e32 v37, v37, v185
	v_add_f32_e32 v38, v38, v185
	v_fma_f32 v70, |v40|, v39, v184
	v_fma_f32 v78, |v36|, v39, v184
	v_add_f32_e32 v40, v40, v185
	v_add_f32_e32 v36, v36, v185
	v_fma_f32 v86, |v37|, v39, v184
	v_fma_f32 v94, |v38|, v39, v184
	v_add_f32_e32 v37, v37, v185
	v_add_f32_e32 v38, v38, v185
	v_fma_f32 v71, |v40|, v39, v184
	v_fma_f32 v79, |v36|, v39, v184
	v_fma_f32 v87, |v37|, v39, v184
	v_fma_f32 v95, |v38|, v39, v184
